# L2 residency in the out/down GEMM epilogue: the read-once residual loads marked non-temporal (timing-only)
# baseline (speedup 1.0000x reference)
.LBB0_455:
	s_lshl_b32 s4, s69, 8
	v_mov_b32_e32 v132, v182
	v_mov_b32_e32 v130, v183
	s_add_i32 s4, s4, s49
	s_nop 0
	v_add_u32_e32 v172, s4, v130
	v_lshrrev_b32_e32 v194, 2, v213
	v_and_b32_e32 v195, 3, v213
	v_lshlrev_b32_e32 v196, 6, v195
	v_lshl_add_u32 v196, v194, 2, v196
	v_and_b32_e32 v197, 15, v213
	v_lshlrev_b32_e32 v197, 4, v197
	v_lshrrev_b32_e32 v198, 4, v213
	v_lshl_add_u32 v197, v198, 2, v197
	v_add_u32_e32 v198, s4, v194
	v_ashrrev_i32_e32 v199, 31, v198
	s_lshl_b32 s4, s68, 8
	s_or_b32 s4, s4, s50
	v_lshl_add_u32 v130, v195, 3, s4
	v_ashrrev_i32_e32 v131, 31, v130
	v_ashrrev_i32_e32 v173, 31, v172
	v_lshlrev_b64 v[168:169], 1, v[130:131]
	v_lshl_add_u64 v[170:171], s[12:13], 0, v[168:169]
	v_lshlrev_b64 v[180:181], 11, v[198:199]
	v_lshl_add_u64 v[130:131], v[170:171], 0, v[180:181]
	global_load_dwordx4 v[188:191], v[130:131], off nt
	global_load_dwordx4 v[154:157], v[130:131], off offset:256 nt
	s_lshl_b32 s4, s68, 2
	s_or_b32 s4, s4, s47
	s_ashr_i32 s5, s4, 31
	s_lshl_b64 s[30:31], s[4:5], 17
	s_mov_b64 s[4:5], 0x8000
	v_lshl_add_u64 v[178:179], v[180:181], 0, s[4:5]
	v_lshl_add_u64 v[130:131], v[170:171], 0, v[178:179]
	global_load_dwordx4 v[150:153], v[130:131], off nt
	global_load_dwordx4 v[146:149], v[130:131], off offset:256 nt
	s_mov_b64 s[4:5], 0x10000
	v_lshl_add_u64 v[176:177], v[180:181], 0, s[4:5]
	v_lshl_add_u64 v[130:131], v[170:171], 0, v[176:177]
	global_load_dwordx4 v[142:145], v[130:131], off nt
	global_load_dwordx4 v[138:141], v[130:131], off offset:256 nt
	s_mov_b64 s[4:5], 0x18000
	v_lshl_add_u64 v[174:175], v[180:181], 0, s[4:5]
	v_lshl_add_u64 v[130:131], v[170:171], 0, v[174:175]
	v_cmp_eq_u32_e32 vcc, 0, v132
	global_load_dwordx4 v[134:137], v[130:131], off nt
	s_nop 0
	global_load_dwordx4 v[130:133], v[130:131], off offset:256 nt
	s_mov_b64 s[4:5], 0x40000
	v_lshl_add_u64 v[234:235], v[180:181], 0, s[4:5]
	v_lshl_add_u64 v[234:235], v[170:171], 0, v[234:235]
	global_load_dwordx4 v[204:207], v[234:235], off nt
	global_load_dwordx4 v[222:225], v[234:235], off offset:256 nt
	s_mov_b64 s[4:5], 0x48000
	v_lshl_add_u64 v[234:235], v[180:181], 0, s[4:5]
	v_lshl_add_u64 v[234:235], v[170:171], 0, v[234:235]
	global_load_dwordx4 v[226:229], v[234:235], off nt
	global_load_dwordx4 v[230:233], v[234:235], off offset:256 nt
	s_mov_b64 s[4:5], 0x50000
	v_lshl_add_u64 v[234:235], v[180:181], 0, s[4:5]
	v_lshl_add_u64 v[234:235], v[170:171], 0, v[234:235]
	global_load_dwordx4 v[238:241], v[234:235], off nt
	global_load_dwordx4 v[250:253], v[234:235], off offset:256 nt
	s_mov_b64 s[4:5], 0x58000
	v_lshl_add_u64 v[234:235], v[180:181], 0, s[4:5]
	v_lshl_add_u64 v[242:243], v[170:171], 0, v[234:235]
	v_lshl_add_u64 v[180:181], s[12:13], 0, v[180:181]
	v_lshl_add_u64 v[180:181], v[180:181], 0, v[168:169]
	s_add_u32 s4, s14, s30
	s_addc_u32 s5, s15, s31
	s_waitcnt vmcnt(6)
	ds_bpermute_b32 v188, v197, v188
	ds_bpermute_b32 v189, v197, v189
	ds_bpermute_b32 v190, v197, v190
	ds_bpermute_b32 v191, v197, v191
	ds_bpermute_b32 v154, v197, v154
	ds_bpermute_b32 v155, v197, v155
	ds_bpermute_b32 v156, v197, v156
	ds_bpermute_b32 v157, v197, v157
	ds_bpermute_b32 v150, v197, v150
	ds_bpermute_b32 v151, v197, v151
	ds_bpermute_b32 v152, v197, v152
	ds_bpermute_b32 v153, v197, v153
	ds_bpermute_b32 v146, v197, v146
	ds_bpermute_b32 v147, v197, v147
	ds_bpermute_b32 v148, v197, v148
	ds_bpermute_b32 v149, v197, v149
	ds_bpermute_b32 v142, v197, v142
	ds_bpermute_b32 v143, v197, v143
	ds_bpermute_b32 v144, v197, v144
	ds_bpermute_b32 v145, v197, v145
	ds_bpermute_b32 v138, v197, v138
	ds_bpermute_b32 v139, v197, v139
	ds_bpermute_b32 v140, v197, v140
	ds_bpermute_b32 v141, v197, v141
	ds_bpermute_b32 v134, v197, v134
	ds_bpermute_b32 v135, v197, v135
	ds_bpermute_b32 v136, v197, v136
	ds_bpermute_b32 v137, v197, v137
	ds_bpermute_b32 v130, v197, v130
	ds_bpermute_b32 v131, v197, v131
	ds_bpermute_b32 v132, v197, v132
	ds_bpermute_b32 v133, v197, v133
	s_waitcnt lgkmcnt(0)
	v_lshlrev_b32_e32 v192, 16, v188
	v_and_b32_e32 v193, 0xffff0000, v188
	v_lshlrev_b32_e32 v188, 16, v189
	v_and_b32_e32 v189, 0xffff0000, v189
	v_pk_add_f32 v[126:127], v[126:127], v[192:193]
	v_pk_add_f32 v[128:129], v[128:129], v[188:189]
	v_cvt_pk_bf16_f32 v126, v126, v127
	v_cvt_pk_bf16_f32 v127, v128, v129
	v_lshlrev_b32_e32 v128, 16, v190
	v_and_b32_e32 v129, 0xffff0000, v190
	v_pk_add_f32 v[122:123], v[122:123], v[128:129]
	s_nop 0
	v_cvt_pk_bf16_f32 v128, v122, v123
	v_lshlrev_b32_e32 v122, 16, v191
	v_and_b32_e32 v123, 0xffff0000, v191
	global_load_dwordx4 v[188:191], v[242:243], off nt
	v_pk_add_f32 v[122:123], v[124:125], v[122:123]
	v_and_b32_e32 v124, 0xffff0000, v127
	v_cvt_pk_bf16_f32 v129, v122, v123
	v_and_b32_e32 v123, 0xffff0000, v126
	v_lshlrev_b32_e32 v122, 16, v126
	v_mul_f32_e32 v123, v123, v123
	v_fmac_f32_e32 v123, v122, v122
	v_lshlrev_b32_e32 v122, 16, v127
	v_mul_f32_e32 v124, v124, v124
	v_fmac_f32_e32 v124, v122, v122
	v_add_f32_e32 v122, v123, v124
	v_and_b32_e32 v124, 0xffff0000, v128
	v_lshlrev_b32_e32 v123, 16, v128
	v_mul_f32_e32 v124, v124, v124
	v_fmac_f32_e32 v124, v123, v123
	v_add_f32_e32 v122, v124, v122
	v_and_b32_e32 v124, 0xffff0000, v129
	v_lshlrev_b32_e32 v123, 16, v129
	v_mul_f32_e32 v124, v124, v124
	v_fmac_f32_e32 v124, v123, v123
	v_add_f32_e32 v124, v124, v122
	v_lshlrev_b32_e32 v122, 16, v154
	v_and_b32_e32 v123, 0xffff0000, v154
	v_pk_add_f32 v[118:119], v[118:119], v[122:123]
	v_lshlrev_b32_e32 v122, 16, v155
	v_and_b32_e32 v123, 0xffff0000, v155
	v_pk_add_f32 v[120:121], v[120:121], v[122:123]
	v_cvt_pk_bf16_f32 v118, v118, v119
	v_cvt_pk_bf16_f32 v119, v120, v121
	v_lshlrev_b32_e32 v120, 16, v156
	v_and_b32_e32 v121, 0xffff0000, v156
	v_pk_add_f32 v[114:115], v[114:115], v[120:121]
	ds_bpermute_b32 v200, v196, v126
	ds_bpermute_b32 v201, v196, v127
	ds_bpermute_b32 v202, v196, v128
	ds_bpermute_b32 v203, v196, v129
	s_waitcnt lgkmcnt(0)
	global_store_dwordx4 v[180:181], v[200:203], off
	v_cvt_pk_bf16_f32 v120, v114, v115
	v_lshlrev_b32_e32 v114, 16, v157
	v_and_b32_e32 v115, 0xffff0000, v157
	global_load_dwordx4 v[154:157], v[242:243], off offset:256 nt
	v_pk_add_f32 v[114:115], v[116:117], v[114:115]
	v_and_b32_e32 v116, 0xffff0000, v119
	v_cvt_pk_bf16_f32 v121, v114, v115
	v_and_b32_e32 v115, 0xffff0000, v118
	v_lshlrev_b32_e32 v114, 16, v118
	v_mul_f32_e32 v115, v115, v115
	v_fmac_f32_e32 v115, v114, v114
	v_lshlrev_b32_e32 v114, 16, v119
	v_mul_f32_e32 v116, v116, v116
	v_fmac_f32_e32 v116, v114, v114
	v_add_f32_e32 v114, v115, v116
	v_and_b32_e32 v116, 0xffff0000, v120
	v_lshlrev_b32_e32 v115, 16, v120
	v_mul_f32_e32 v116, v116, v116
	v_fmac_f32_e32 v116, v115, v115
	v_add_f32_e32 v114, v116, v114
	v_and_b32_e32 v116, 0xffff0000, v121
	v_lshlrev_b32_e32 v115, 16, v121
	v_mul_f32_e32 v116, v116, v116
	v_fmac_f32_e32 v116, v115, v115
	v_add_f32_e32 v114, v116, v114
	v_lshlrev_b32_e32 v116, 16, v150
	v_and_b32_e32 v117, 0xffff0000, v150
	v_pk_add_f32 v[110:111], v[110:111], v[116:117]
	v_lshlrev_b32_e32 v116, 16, v151
	v_and_b32_e32 v117, 0xffff0000, v151
	v_pk_add_f32 v[112:113], v[112:113], v[116:117]
	v_cvt_pk_bf16_f32 v110, v110, v111
	v_cvt_pk_bf16_f32 v111, v112, v113
	v_lshlrev_b32_e32 v112, 16, v152
	v_and_b32_e32 v113, 0xffff0000, v152
	v_pk_add_f32 v[106:107], v[106:107], v[112:113]
	ds_bpermute_b32 v200, v196, v118
	ds_bpermute_b32 v201, v196, v119
	ds_bpermute_b32 v202, v196, v120
	ds_bpermute_b32 v203, v196, v121
	s_waitcnt lgkmcnt(0)
	global_store_dwordx4 v[180:181], v[200:203], off offset:256
	v_cvt_pk_bf16_f32 v112, v106, v107
	v_lshlrev_b32_e32 v106, 16, v153
	v_and_b32_e32 v107, 0xffff0000, v153
	v_pk_add_f32 v[106:107], v[108:109], v[106:107]
	v_add_f32_e32 v118, v124, v114
	v_cvt_pk_bf16_f32 v113, v106, v107
	v_lshlrev_b32_e32 v106, 16, v146
	v_and_b32_e32 v107, 0xffff0000, v146
	v_pk_add_f32 v[102:103], v[102:103], v[106:107]
	v_lshlrev_b32_e32 v106, 16, v147
	v_and_b32_e32 v107, 0xffff0000, v147
	v_pk_add_f32 v[104:105], v[104:105], v[106:107]
	v_cvt_pk_bf16_f32 v102, v102, v103
	v_cvt_pk_bf16_f32 v103, v104, v105
	v_lshlrev_b32_e32 v104, 16, v148
	v_and_b32_e32 v105, 0xffff0000, v148
	v_pk_add_f32 v[94:95], v[94:95], v[104:105]
	v_lshl_add_u64 v[114:115], s[12:13], 0, v[178:179]
	v_cvt_pk_bf16_f32 v104, v94, v95
	v_lshlrev_b32_e32 v94, 16, v149
	v_and_b32_e32 v95, 0xffff0000, v149
	v_pk_add_f32 v[94:95], v[96:97], v[94:95]
	v_lshlrev_b32_e32 v96, 16, v143
	v_cvt_pk_bf16_f32 v105, v94, v95
	v_lshl_add_u64 v[94:95], s[12:13], 0, v[176:177]
	v_lshl_add_u64 v[106:107], v[94:95], 0, v[168:169]
	v_lshlrev_b32_e32 v94, 16, v142
	v_and_b32_e32 v95, 0xffff0000, v142
	v_and_b32_e32 v97, 0xffff0000, v143
	v_pk_add_f32 v[94:95], v[98:99], v[94:95]
	v_pk_add_f32 v[96:97], v[100:101], v[96:97]
	v_cvt_pk_bf16_f32 v94, v94, v95
	v_cvt_pk_bf16_f32 v95, v96, v97
	v_lshlrev_b32_e32 v96, 16, v144
	v_and_b32_e32 v97, 0xffff0000, v144
	v_pk_add_f32 v[90:91], v[90:91], v[96:97]
	v_lshl_add_u64 v[114:115], v[114:115], 0, v[168:169]
	v_cvt_pk_bf16_f32 v96, v90, v91
	v_lshlrev_b32_e32 v90, 16, v145
	v_and_b32_e32 v91, 0xffff0000, v145
	v_pk_add_f32 v[90:91], v[92:93], v[90:91]
	v_lshl_add_u64 v[98:99], v[172:173], 2, s[4:5]
	v_cvt_pk_bf16_f32 v97, v90, v91
	v_lshlrev_b32_e32 v90, 16, v138
	v_and_b32_e32 v91, 0xffff0000, v138
	v_pk_add_f32 v[86:87], v[86:87], v[90:91]
	v_lshlrev_b32_e32 v90, 16, v139
	v_and_b32_e32 v91, 0xffff0000, v139
	v_pk_add_f32 v[88:89], v[88:89], v[90:91]
	v_cvt_pk_bf16_f32 v86, v86, v87
	v_cvt_pk_bf16_f32 v87, v88, v89
	v_lshlrev_b32_e32 v88, 16, v140
	v_and_b32_e32 v89, 0xffff0000, v140
	v_pk_add_f32 v[78:79], v[78:79], v[88:89]
	ds_bpermute_b32 v200, v196, v110
	ds_bpermute_b32 v201, v196, v111
	ds_bpermute_b32 v202, v196, v112
	ds_bpermute_b32 v203, v196, v113
	s_waitcnt lgkmcnt(0)
	global_store_dwordx4 v[114:115], v[200:203], off
	v_cvt_pk_bf16_f32 v88, v78, v79
	v_lshlrev_b32_e32 v78, 16, v141
	v_and_b32_e32 v79, 0xffff0000, v141
	v_pk_add_f32 v[78:79], v[80:81], v[78:79]
	v_lshlrev_b32_e32 v80, 16, v135
	v_cvt_pk_bf16_f32 v89, v78, v79
	v_lshl_add_u64 v[78:79], s[12:13], 0, v[174:175]
	v_lshl_add_u64 v[90:91], v[78:79], 0, v[168:169]
	v_lshlrev_b32_e32 v78, 16, v134
	v_and_b32_e32 v79, 0xffff0000, v134
	v_and_b32_e32 v81, 0xffff0000, v135
	v_pk_add_f32 v[78:79], v[82:83], v[78:79]
	v_pk_add_f32 v[80:81], v[84:85], v[80:81]
	v_cvt_pk_bf16_f32 v78, v78, v79
	v_cvt_pk_bf16_f32 v79, v80, v81
	v_lshlrev_b32_e32 v80, 16, v136
	v_and_b32_e32 v81, 0xffff0000, v136
	v_pk_add_f32 v[74:75], v[74:75], v[80:81]
	ds_bpermute_b32 v200, v196, v102
	ds_bpermute_b32 v201, v196, v103
	ds_bpermute_b32 v202, v196, v104
	ds_bpermute_b32 v203, v196, v105
	s_waitcnt lgkmcnt(0)
	global_store_dwordx4 v[114:115], v[200:203], off offset:256
	v_cvt_pk_bf16_f32 v80, v74, v75
	v_lshlrev_b32_e32 v74, 16, v137
	v_and_b32_e32 v75, 0xffff0000, v137
	v_pk_add_f32 v[74:75], v[76:77], v[74:75]
	ds_bpermute_b32 v200, v196, v94
	ds_bpermute_b32 v201, v196, v95
	ds_bpermute_b32 v202, v196, v96
	ds_bpermute_b32 v203, v196, v97
	s_waitcnt lgkmcnt(0)
	global_store_dwordx4 v[106:107], v[200:203], off
	v_cvt_pk_bf16_f32 v81, v74, v75
	v_lshlrev_b32_e32 v74, 16, v130
	v_and_b32_e32 v75, 0xffff0000, v130
	v_pk_add_f32 v[70:71], v[70:71], v[74:75]
	v_lshlrev_b32_e32 v74, 16, v131
	v_and_b32_e32 v75, 0xffff0000, v131
	v_pk_add_f32 v[72:73], v[72:73], v[74:75]
	v_cvt_pk_bf16_f32 v70, v70, v71
	v_cvt_pk_bf16_f32 v71, v72, v73
	v_lshlrev_b32_e32 v72, 16, v132
	v_and_b32_e32 v73, 0xffff0000, v132
	v_pk_add_f32 v[66:67], v[66:67], v[72:73]
	ds_bpermute_b32 v200, v196, v86
	ds_bpermute_b32 v201, v196, v87
	ds_bpermute_b32 v202, v196, v88
	ds_bpermute_b32 v203, v196, v89
	s_waitcnt lgkmcnt(0)
	global_store_dwordx4 v[106:107], v[200:203], off offset:256
	v_cvt_pk_bf16_f32 v72, v66, v67
	v_lshlrev_b32_e32 v66, 16, v133
	v_and_b32_e32 v67, 0xffff0000, v133
	v_pk_add_f32 v[66:67], v[68:69], v[66:67]
	ds_bpermute_b32 v200, v196, v78
	ds_bpermute_b32 v201, v196, v79
	ds_bpermute_b32 v202, v196, v80
	ds_bpermute_b32 v203, v196, v81
	s_waitcnt lgkmcnt(0)
	global_store_dwordx4 v[90:91], v[200:203], off
	v_cvt_pk_bf16_f32 v73, v66, v67
	ds_bpermute_b32 v66, v185, v118
	ds_bpermute_b32 v200, v196, v70
	ds_bpermute_b32 v201, v196, v71
	ds_bpermute_b32 v202, v196, v72
	ds_bpermute_b32 v203, v196, v73
	s_waitcnt lgkmcnt(0)
	global_store_dwordx4 v[90:91], v[200:203], off offset:256
	s_waitcnt lgkmcnt(0)
	v_add_f32_e32 v66, v118, v66
	ds_bpermute_b32 v67, v186, v66
	s_and_saveexec_b64 s[30:31], vcc
	s_cbranch_execz .LBB0_457
	s_waitcnt lgkmcnt(0)
	v_add_f32_e32 v66, v66, v67
	global_store_dword v[98:99], v66, off
